# XCD-local seams, start stagger 6us/XCD (XCD_SLEEP=192)
# baseline (speedup 1.0000x reference)
.Lxl_stag_loop:
	s_sleep 127
	s_sleep 65
	s_add_i32 s101, s101, -1
	s_cmp_lg_u32 s101, 0
	s_cbranch_scc1 .Lxl_stag_loop
